# rowpass B: row loop software-pipelined by one row (next row's 9 loads issued at the row top into shadow registers)
# baseline (speedup 1.0000x reference)
.LBB0_134:
	s_cmp_gt_i32 s72, 11
	s_mov_b64 s[4:5], -1
	s_cbranch_scc0 .LBB0_146
	v_readlane_b32 s0, v252, 10
	v_readlane_b32 s10, v254, 58
	s_add_i32 s16, s10, s0
	s_mov_b64 s[6:7], s[94:95]
	s_mov_b64 s[8:9], s[92:93]
	s_mov_b64 s[4:5], s[92:93]
	s_cmpk_gt_i32 s16, 0x43ff
	s_cbranch_scc1 .LBB0_145
	v_lshlrev_b32_e32 v0, 3, v192
	v_and_b32_e32 v2, 24, v0
	v_lshlrev_b32_e32 v152, 3, v2
	v_lshl_add_u64 v[0:1], s[6:7], 0, v[152:153]
	s_mov_b64 s[10:11], 0x4600000
	v_lshlrev_b32_e32 v152, 2, v2
	v_lshl_add_u64 v[16:17], v[0:1], 0, s[10:11]
	v_lshl_add_u64 v[0:1], s[8:9], 0, v[152:153]
	v_lshlrev_b32_e32 v152, 4, v192
	v_lshl_add_u64 v[2:3], s[4:5], 0, v[152:153]
	s_mov_b64 s[4:5], 0xad00000
	v_lshl_add_u64 v[18:19], v[2:3], 0, s[4:5]
	v_or_b32_e32 v2, 64, v192
	s_movk_i32 s0, 0x50
	v_cmp_gt_u32_e64 s[4:5], s0, v2
	v_lshlrev_b32_e32 v2, 6, v2
	s_bfe_u32 s17, s69, 0x30006
	v_and_b32_e32 v152, 0x1f00, v2
	s_bitset1_b32 s17, 11
	v_lshl_add_u64 v[20:21], v[0:1], 0, v[152:153]
	v_mov_b32_e32 v0, 0xc700a00
	s_mul_i32 s8, s16, 0xc00
	v_lshl_or_b32 v152, v192, 3, v0
	s_mul_hi_i32 s0, s16, 0xc00
	s_add_u32 s6, s6, s8
	v_lshlrev_b32_e32 v0, 4, v191
	s_addc_u32 s7, s7, s0
	v_and_b32_e32 v0, 48, v0
	v_lshlrev_b32_e32 v1, 5, v191
	s_movk_i32 s0, 0x780
	v_and_or_b32 v22, v1, s0, v0
	v_or_b32_e32 v24, 0x800, v22
	v_mov_b32_e32 v25, v153
	v_mov_b32_e32 v23, v153
	s_and_b32 s19, s16, 0x7ff
	s_cmpk_lt_i32 s16, 0x4000
	s_cselect_b32 s19, s19, s17
	s_lshl_b32 s20, s19, 8
	s_mov_b32 s21, 0
	v_lshl_add_u64 v[108:109], v[16:17], 0, s[20:21]
	v_lshl_add_u64 v[110:111], s[6:7], 0, v[22:23]
	s_mov_b32 s20, 0xc700000
	s_mov_b32 s21, 0
	v_lshl_add_u64 v[110:111], v[110:111], 0, s[20:21]
	global_load_dwordx4 v[72:75], v[110:111], off
	global_load_dwordx4 v[76:79], v[110:111], off offset:64
	global_load_dwordx4 v[80:83], v[108:109], off
	global_load_dwordx4 v[84:87], v[108:109], off offset:16
	global_load_dwordx4 v[88:91], v[108:109], off offset:32
	global_load_dwordx4 v[92:95], v[108:109], off offset:48
	global_load_dwordx4 v[96:99], v[110:111], off offset:2048
	global_load_dwordx4 v[100:103], v[110:111], off offset:2112
	global_load_dwordx4 v[104:107], v[108:109], off
	s_branch .LBB0_138

.LBB0_138:
	s_and_b32 s0, s16, 0x7ff
	s_cmpk_lt_i32 s16, 0x4000
	s_cselect_b64 s[8:9], -1, 0
	s_and_b64 s[10:11], s[8:9], exec
	s_cselect_b32 s12, s0, s17
	s_cmpk_gt_u32 s0, 0x77f
	s_cselect_b64 s[10:11], -1, 0
	s_and_b64 s[10:11], s[8:9], s[10:11]
	s_ashr_i32 s8, s16, 4
	s_and_b32 s8, s8, 0xffffff80
	s_add_i32 s8, s0, s8
	s_lshl_b32 s0, s12, 8
	v_lshl_add_u64 v[26:27], v[16:17], 0, s[0:1]
	v_lshl_add_u64 v[0:1], s[6:7], 0, v[22:23]
	s_mov_b32 s0, 0xc700000
	v_add_co_u32_e32 v8, vcc, s0, v0
	s_addk_i32 s8, 0xf880
	s_nop 0
	v_addc_co_u32_e32 v9, vcc, 0, v1, vcc
	s_ashr_i32 s9, s8, 31
	s_lshl_b64 s[8:9], s[8:9], 10
	s_mov_b64 s[14:15], -1
	s_waitcnt vmcnt(0) lgkmcnt(0)
	v_mov_b64_e32 v[4:5], v[72:73]
	v_mov_b64_e32 v[6:7], v[74:75]
	v_mov_b64_e32 v[0:1], v[76:77]
	v_mov_b64_e32 v[2:3], v[78:79]
	v_mov_b64_e32 v[10:11], v[80:81]
	v_mov_b64_e32 v[12:13], v[82:83]
	v_mov_b64_e32 v[60:61], v[84:85]
	v_mov_b64_e32 v[62:63], v[86:87]
	v_mov_b64_e32 v[64:65], v[88:89]
	v_mov_b64_e32 v[66:67], v[90:91]
	v_mov_b64_e32 v[68:69], v[92:93]
	v_mov_b64_e32 v[70:71], v[94:95]
	v_mov_b64_e32 v[44:45], v[96:97]
	v_mov_b64_e32 v[46:47], v[98:99]
	v_mov_b64_e32 v[48:49], v[100:101]
	v_mov_b64_e32 v[50:51], v[102:103]
	v_mov_b64_e32 v[52:53], v[104:105]
	v_mov_b64_e32 v[54:55], v[106:107]
	s_add_i32 s18, s16, s80
	s_and_b32 s19, s18, 0x7ff
	s_cmpk_lt_i32 s18, 0x4000
	s_cselect_b32 s19, s19, s17
	s_lshl_b32 s20, s19, 8
	s_mov_b32 s21, 0
	v_lshl_add_u64 v[108:109], v[16:17], 0, s[20:21]
	s_mul_i32 s20, s3, 0x6000
	s_add_u32 s22, s6, s20
	s_mul_hi_i32 s20, s80, 0xc00
	s_addc_u32 s23, s7, s20
	v_lshl_add_u64 v[110:111], s[22:23], 0, v[22:23]
	s_mov_b32 s20, 0xc700000
	s_mov_b32 s21, 0
	v_lshl_add_u64 v[110:111], v[110:111], 0, s[20:21]
	global_load_dwordx4 v[72:75], v[110:111], off
	global_load_dwordx4 v[76:79], v[110:111], off offset:64
	global_load_dwordx4 v[80:83], v[108:109], off
	global_load_dwordx4 v[84:87], v[108:109], off offset:16
	global_load_dwordx4 v[88:91], v[108:109], off offset:32
	global_load_dwordx4 v[92:95], v[108:109], off offset:48
	global_load_dwordx4 v[96:99], v[110:111], off offset:2048
	global_load_dwordx4 v[100:103], v[110:111], off offset:2112
	global_load_dwordx4 v[104:107], v[108:109], off
	v_lshlrev_b32_e32 v14, 16, v4
	v_lshlrev_b32_e32 v28, 16, v0
	v_and_b32_e32 v29, 0xffff0000, v0
	v_mov_b32_e32 v30, v10
	v_mov_b32_e32 v31, v12
	v_mov_b32_e32 v12, v11
	v_and_b32_e32 v15, 0xffff0000, v4
	v_pk_mul_f32 v[10:11], v[12:13], v[28:29]
	v_pk_mul_f32 v[28:29], v[30:31], v[28:29]
	v_pk_fma_f32 v[10:11], v[30:31], v[14:15], v[10:11] neg_lo:[0,0,1] neg_hi:[0,0,1]
	v_pk_fma_f32 v[12:13], v[12:13], v[14:15], v[28:29]
	v_cvt_pk_bf16_f32 v4, v10, v11
	v_cvt_pk_bf16_f32 v0, v12, v13
	v_mov_b32_e32 v10, v60
	v_mov_b32_e32 v11, v61
	v_mov_b32_e32 v12, v62
	v_mov_b32_e32 v13, v63
	v_lshlrev_b32_e32 v28, 16, v1
	v_and_b32_e32 v29, 0xffff0000, v1
	v_lshlrev_b32_e32 v14, 16, v5
	v_and_b32_e32 v15, 0xffff0000, v5
	v_mov_b32_e32 v30, v10
	v_mov_b32_e32 v31, v12
	v_mov_b32_e32 v12, v11
	v_pk_mul_f32 v[10:11], v[12:13], v[28:29]
	v_pk_mul_f32 v[28:29], v[30:31], v[28:29]
	v_pk_fma_f32 v[10:11], v[30:31], v[14:15], v[10:11] neg_lo:[0,0,1] neg_hi:[0,0,1]
	v_pk_fma_f32 v[12:13], v[12:13], v[14:15], v[28:29]
	v_cvt_pk_bf16_f32 v5, v10, v11
	v_cvt_pk_bf16_f32 v1, v12, v13
	v_mov_b32_e32 v10, v64
	v_mov_b32_e32 v11, v65
	v_mov_b32_e32 v12, v66
	v_mov_b32_e32 v13, v67
	v_lshlrev_b32_e32 v28, 16, v2
	v_and_b32_e32 v29, 0xffff0000, v2
	v_lshlrev_b32_e32 v14, 16, v6
	v_and_b32_e32 v15, 0xffff0000, v6
	v_mov_b32_e32 v30, v10
	v_mov_b32_e32 v31, v12
	v_mov_b32_e32 v12, v11
	v_pk_mul_f32 v[10:11], v[12:13], v[28:29]
	v_pk_mul_f32 v[28:29], v[30:31], v[28:29]
	v_pk_fma_f32 v[10:11], v[30:31], v[14:15], v[10:11] neg_lo:[0,0,1] neg_hi:[0,0,1]
	v_pk_fma_f32 v[12:13], v[12:13], v[14:15], v[28:29]
	v_cvt_pk_bf16_f32 v6, v10, v11
	v_cvt_pk_bf16_f32 v2, v12, v13
	v_mov_b32_e32 v10, v68
	v_mov_b32_e32 v11, v69
	v_mov_b32_e32 v12, v70
	v_mov_b32_e32 v13, v71
	v_lshlrev_b32_e32 v28, 16, v3
	v_and_b32_e32 v29, 0xffff0000, v3
	v_lshlrev_b32_e32 v14, 16, v7
	v_and_b32_e32 v15, 0xffff0000, v7
	v_mov_b32_e32 v31, v12
	v_mov_b32_e32 v12, v11
	v_mov_b32_e32 v30, v10
	v_pk_mul_f32 v[10:11], v[12:13], v[28:29]
	v_pk_mul_f32 v[28:29], v[30:31], v[28:29]
	v_pk_fma_f32 v[10:11], v[30:31], v[14:15], v[10:11] neg_lo:[0,0,1] neg_hi:[0,0,1]
	v_pk_fma_f32 v[12:13], v[12:13], v[14:15], v[28:29]
	v_cvt_pk_bf16_f32 v7, v10, v11
	v_cvt_pk_bf16_f32 v3, v12, v13
	flat_store_dwordx4 v[8:9], v[4:7]
	flat_store_dwordx4 v[8:9], v[0:3] offset:64
	s_and_saveexec_b64 s[12:13], s[4:5]
	s_cbranch_execz .LBB0_142
	v_lshl_add_u64 v[0:1], s[6:7], 0, v[24:25]
	v_add_co_u32_e32 v28, vcc, 0xc700000, v0
	s_mov_b64 s[14:15], 0
	s_nop 0
	v_addc_co_u32_e32 v29, vcc, 0, v1, vcc
	v_mov_b64_e32 v[12:13], v[44:45]
	v_mov_b64_e32 v[14:15], v[46:47]
	v_mov_b64_e32 v[8:9], v[48:49]
	v_mov_b64_e32 v[10:11], v[50:51]
	v_mov_b64_e32 v[0:1], v[52:53]
	v_mov_b64_e32 v[2:3], v[54:55]
	v_mov_b64_e32 v[36:37], v[60:61]
	v_mov_b64_e32 v[38:39], v[62:63]
	s_and_b64 vcc, exec, s[10:11]
	v_lshlrev_b32_e32 v6, 16, v12
	v_lshlrev_b32_e32 v30, 16, v8
	v_and_b32_e32 v31, 0xffff0000, v8
	v_mov_b32_e32 v33, v2
	v_mov_b32_e32 v2, v1
	v_and_b32_e32 v7, 0xffff0000, v12
	v_mov_b32_e32 v32, v0
	v_pk_mul_f32 v[0:1], v[2:3], v[30:31]
	v_lshlrev_b32_e32 v8, 16, v9
	v_pk_fma_f32 v[4:5], v[32:33], v[6:7], v[0:1] neg_lo:[0,0,1] neg_hi:[0,0,1]
	v_pk_mul_f32 v[0:1], v[32:33], v[30:31]
	v_and_b32_e32 v9, 0xffff0000, v9
	v_pk_fma_f32 v[0:1], v[2:3], v[6:7], v[0:1]
	v_lshlrev_b32_e32 v2, 16, v13
	v_and_b32_e32 v3, 0xffff0000, v13
	v_mov_b32_e32 v12, v36
	v_mov_b32_e32 v13, v38
	v_mov_b32_e32 v38, v37
	v_pk_mul_f32 v[6:7], v[38:39], v[8:9]
	v_pk_mul_f32 v[8:9], v[12:13], v[8:9]
	v_pk_fma_f32 v[6:7], v[12:13], v[2:3], v[6:7] neg_lo:[0,0,1] neg_hi:[0,0,1]
	v_pk_fma_f32 v[2:3], v[38:39], v[2:3], v[8:9]
	v_mov_b32_e32 v36, v64
	v_mov_b32_e32 v37, v65
	v_mov_b32_e32 v38, v66
	v_mov_b32_e32 v39, v67
	v_lshlrev_b32_e32 v32, 16, v10
	v_and_b32_e32 v33, 0xffff0000, v10
	v_lshlrev_b32_e32 v8, 16, v14
	v_and_b32_e32 v9, 0xffff0000, v14
	v_lshlrev_b32_e32 v10, 16, v11
	v_and_b32_e32 v11, 0xffff0000, v11
	v_cvt_pk_bf16_f32 v30, v4, v5
	v_cvt_pk_bf16_f32 v31, v6, v7
	v_cvt_pk_bf16_f32 v34, v0, v1
	v_cvt_pk_bf16_f32 v35, v2, v3
	v_mov_b32_e32 v40, v36
	v_mov_b32_e32 v41, v38
	v_mov_b32_e32 v38, v37
	v_pk_mul_f32 v[12:13], v[38:39], v[32:33]
	v_pk_mul_f32 v[32:33], v[40:41], v[32:33]
	v_pk_fma_f32 v[12:13], v[40:41], v[8:9], v[12:13] neg_lo:[0,0,1] neg_hi:[0,0,1]
	v_pk_fma_f32 v[8:9], v[38:39], v[8:9], v[32:33]
	v_mov_b32_e32 v38, v68
	v_mov_b32_e32 v39, v69
	v_mov_b32_e32 v40, v70
	v_mov_b32_e32 v41, v71
	v_lshlrev_b32_e32 v26, 16, v15
	v_and_b32_e32 v27, 0xffff0000, v15
	v_cvt_pk_bf16_f32 v32, v12, v13
	v_cvt_pk_bf16_f32 v36, v8, v9
	v_mov_b32_e32 v43, v40
	v_mov_b32_e32 v40, v39
	v_mov_b32_e32 v42, v38
	v_pk_mul_f32 v[14:15], v[40:41], v[10:11]
	v_pk_mul_f32 v[10:11], v[42:43], v[10:11]
	v_pk_fma_f32 v[14:15], v[42:43], v[26:27], v[14:15] neg_lo:[0,0,1] neg_hi:[0,0,1]
	v_pk_fma_f32 v[10:11], v[40:41], v[26:27], v[10:11]
	v_cvt_pk_bf16_f32 v33, v14, v15
	v_cvt_pk_bf16_f32 v37, v10, v11
	flat_store_dwordx4 v[28:29], v[30:33]
	flat_store_dwordx4 v[28:29], v[34:37] offset:64
	s_cbranch_vccz .LBB0_141
	v_lshl_add_u64 v[26:27], v[20:21], 0, s[8:9]
	v_add_co_u32_e32 v26, vcc, 0xabff000, v26
	s_mov_b64 s[14:15], -1
	s_nop 0
	v_addc_co_u32_e32 v27, vcc, 0, v27, vcc
	flat_store_dwordx4 v[26:27], v[4:7]
	flat_store_dwordx4 v[26:27], v[12:15] offset:16
	flat_store_dwordx4 v[26:27], v[0:3] offset:128
	flat_store_dwordx4 v[26:27], v[8:11] offset:144
